# v63 + grid barrier: the release-generation atomic issued with sc1 (performed at the memory side so pollers on other XCDs see it sooner)
# speedup vs baseline: 1.0019x; 1.0002x over previous
; __device__ __forceinline__ unsigned xb_add(unsigned* p, unsigned v) { return __hip_atomic_fetch_add(p, v, __ATOMIC_RELAXED, __HIP_MEMORY_SCOPE_AGENT); }
; __device__ __forceinline__ void xcd_barrier(const XcdBarrier& b) {
;     ...
;             if (og + 1u == (tg + 1u) * nx) xb_add(&bar[XB_TOPGEN], 1u);
.LBB0_242:
	s_or_b64 exec, exec, s[12:13]
	s_and_saveexec_b64 s[10:11], s[14:15]
	s_cbranch_execz .LBB0_244
	global_atomic_add v[2:3], v252, off sc1

; __device__ __forceinline__ unsigned xb_add(unsigned* p, unsigned v) { return __hip_atomic_fetch_add(p, v, __ATOMIC_RELAXED, __HIP_MEMORY_SCOPE_AGENT); }
; __device__ __forceinline__ void xcd_barrier(const XcdBarrier& b) {
;     ...
;             if (og + 1u == (tg + 1u) * nx) xb_add(&bar[XB_TOPGEN], 1u);
.LBB0_599:
	s_or_b64 exec, exec, s[10:11]
	s_and_saveexec_b64 s[8:9], s[12:13]
	s_cbranch_execz .LBB0_601
	global_atomic_add v[2:3], v252, off sc1

; __device__ __forceinline__ unsigned xb_add(unsigned* p, unsigned v) { return __hip_atomic_fetch_add(p, v, __ATOMIC_RELAXED, __HIP_MEMORY_SCOPE_AGENT); }
; __device__ __forceinline__ void xcd_barrier(const XcdBarrier& b) {
;     ...
;             if (og + 1u == (tg + 1u) * nx) xb_add(&bar[XB_TOPGEN], 1u);
.LBB0_1498:
	s_or_b64 exec, exec, s[8:9]
	s_and_saveexec_b64 s[4:5], s[12:13]
	s_cbranch_execz .LBB0_1500
	v_mov_b32_e32 v2, 1
	global_atomic_add v[0:1], v2, off sc1
